# final-phase f32 output stores (full-sector form) switched to nt streaming policy: no L2 pollution for straggling K-loops, smaller end-of-kernel write-back tail
# speedup vs baseline: 1.0112x; 1.0112x over previous
;   DI void operator()(g8::Acc& acc, int pm, int pn, int wr, int wc, int fr, int fq) const {
;     ...
; #pragma unroll
;     for (int ai = 0; ai < 2; ++ai)
; #pragma unroll
;       for (int m = 0; m < 4; ++m) {
;         const int row = pm * BM + ai * HALF + wr * 64 + m * 16 + fr;
;         const float rs = rsqrtf(__hip_atomic_load(ssq + row, __ATOMIC_RELAXED, __HIP_MEMORY_SCOPE_AGENT) * (1.0f / DM) + RMS_EPS);
; #pragma unroll
;         for (int bj = 0; bj < 2; ++bj) {
;           const int col8 = pn * BM + wc * 64 + bj * 32 + fq * 8; const unsigned eo = (unsigned)row * DM + (unsigned)col8;
;           gst<f32x4>(outf, eo * 4u, acc[ai][bj][m][0] * rs * gld<f32x4>(g, (unsigned)col8 * 4u));
;           gst<f32x4>(outf, eo * 4u + 16u, acc[ai][bj][m][1] * rs * gld<f32x4>(g, (unsigned)col8 * 4u + 16u));
;         }
;       }
.LBB0_930:
	s_or_b64 exec, exec, s[42:43]
	v_mbcnt_lo_u32_b32 v202, -1, 0
	v_mbcnt_hi_u32_b32 v202, -1, v202
	v_and_b32_e32 v202, 48, v202
	v_lshl_add_u64 v[164:165], v[140:141], 2, s[16:17]
	s_barrier
	global_load_dword v168, v[164:165], off sc1
	v_lshl_or_b32 v141, s38, 10, v158
	global_load_dwordx4 v[176:179], v141, s[70:71]
	global_load_dwordx4 v[180:183], v141, s[70:71] offset:16
	global_load_dwordx4 v[184:187], v141, s[70:71] offset:128
	global_load_dwordx4 v[188:191], v141, s[70:71] offset:144
	v_lshl_add_u64 v[200:201], v[116:117], 2, s[16:17]
	global_load_dword v193, v[200:201], off sc1
	v_lshl_add_u64 v[200:201], v[100:101], 2, s[16:17]
	global_load_dword v194, v[200:201], off sc1
	v_lshl_add_u64 v[200:201], v[84:85], 2, s[16:17]
	global_load_dword v195, v[200:201], off sc1
	v_lshl_add_u64 v[200:201], v[68:69], 2, s[16:17]
	global_load_dword v196, v[200:201], off sc1
	v_lshl_add_u64 v[200:201], v[52:53], 2, s[16:17]
	global_load_dword v197, v[200:201], off sc1
	v_lshl_add_u64 v[200:201], v[36:37], 2, s[16:17]
	global_load_dword v198, v[200:201], off sc1
	v_lshl_add_u64 v[200:201], v[20:21], 2, s[16:17]
	global_load_dword v199, v[200:201], off sc1
	s_waitcnt vmcnt(0)
	s_mov_b64 s[0:1], -1
	v_fmamk_f32 v168, v168, 0x3a800000, v163
	v_mul_f32_e32 v169, 0x4b800000, v168
	v_cmp_gt_f32_e32 vcc, s51, v168
	s_nop 1
	v_cndmask_b32_e32 v168, v168, v169, vcc
	v_rsq_f32_e32 v168, v168
	v_lshlrev_b32_e32 v169, 12, v140
	v_add_u32_e32 v170, v141, v169
	v_mul_f32_e32 v140, 0x45800000, v168
	v_cndmask_b32_e32 v140, v168, v140, vcc
	v_pk_mul_f32 v[142:143], v[142:143], v[140:141] op_sel_hi:[1,0]
	v_pk_mul_f32 v[126:127], v[126:127], v[140:141] op_sel_hi:[1,0]
	v_pk_mul_f32 v[164:165], v[176:177], v[142:143]
	v_pk_mul_f32 v[166:167], v[178:179], v[126:127]
	v_mov_b32_e32 v204, v164
	v_mov_b32_e32 v205, v165
	v_mov_b32_e32 v206, v166
	v_mov_b32_e32 v207, v167
	v_pk_mul_f32 v[126:127], v[122:123], v[140:141] op_sel_hi:[1,0]
	v_pk_mul_f32 v[122:123], v[124:125], v[140:141] op_sel_hi:[1,0]
	v_pk_mul_f32 v[142:143], v[118:119], v[140:141] op_sel_hi:[1,0]
	v_pk_mul_f32 v[118:119], v[120:121], v[140:141] op_sel_hi:[1,0]
	v_pk_mul_f32 v[114:115], v[114:115], v[140:141] op_sel_hi:[1,0]
	v_pk_mul_f32 v[112:113], v[112:113], v[140:141] op_sel_hi:[1,0]
	v_pk_mul_f32 v[122:123], v[180:181], v[122:123]
	v_pk_mul_f32 v[124:125], v[182:183], v[126:127]
	s_nop 1
	v_permlane16_swap_b32_e32 v204, v122
	v_permlane16_swap_b32_e32 v205, v123
	v_permlane16_swap_b32_e32 v206, v124
	v_permlane16_swap_b32_e32 v207, v125
	v_permlane32_swap_b32_e32 v204, v122
	v_permlane32_swap_b32_e32 v205, v123
	v_permlane32_swap_b32_e32 v206, v124
	v_permlane32_swap_b32_e32 v207, v125
	v_sub_u32_e32 v203, v170, v202
	global_store_dwordx4 v203, v[204:207], s[72:73] nt
	global_store_dwordx4 v203, v[122:125], s[72:73] offset:64 nt
	s_nop 1
	v_pk_mul_f32 v[118:119], v[184:185], v[118:119]
	v_or_b32_e32 v122, 0x80, v141
	v_add_u32_e32 v123, v122, v169
	v_pk_mul_f32 v[120:121], v[186:187], v[142:143]
	v_mov_b32_e32 v204, v118
	v_mov_b32_e32 v205, v119
	v_mov_b32_e32 v206, v120
	v_mov_b32_e32 v207, v121
	v_pk_mul_f32 v[112:113], v[188:189], v[112:113]
	v_pk_mul_f32 v[114:115], v[190:191], v[114:115]
	s_nop 1
	v_permlane16_swap_b32_e32 v204, v112
	v_permlane16_swap_b32_e32 v205, v113
	v_permlane16_swap_b32_e32 v206, v114
	v_permlane16_swap_b32_e32 v207, v115
	v_permlane32_swap_b32_e32 v204, v112
	v_permlane32_swap_b32_e32 v205, v113
	v_permlane32_swap_b32_e32 v206, v114
	v_permlane32_swap_b32_e32 v207, v115
	v_sub_u32_e32 v203, v123, v202
	global_store_dwordx4 v203, v[204:207], s[72:73] nt
	global_store_dwordx4 v203, v[112:115], s[72:73] offset:64 nt
	s_nop 1
	s_nop 0
	v_lshlrev_b32_e32 v120, 12, v116
	v_add_u32_e32 v121, v120, v141
	v_fmamk_f32 v117, v193, 0x3a800000, v163
	v_mul_f32_e32 v118, 0x4b800000, v117
	v_cmp_gt_f32_e32 vcc, s51, v117
	s_nop 1
	v_cndmask_b32_e32 v117, v117, v118, vcc
	v_rsq_f32_e32 v117, v117
	s_nop 0
	v_mul_f32_e32 v116, 0x45800000, v117
	v_cndmask_b32_e32 v116, v117, v116, vcc
	v_pk_mul_f32 v[118:119], v[144:145], v[116:117] op_sel_hi:[1,0]
	v_pk_mul_f32 v[110:111], v[110:111], v[116:117] op_sel_hi:[1,0]
	v_pk_mul_f32 v[112:113], v[176:177], v[118:119]
	v_pk_mul_f32 v[114:115], v[178:179], v[110:111]
	v_mov_b32_e32 v204, v112
	v_mov_b32_e32 v205, v113
	v_mov_b32_e32 v206, v114
	v_mov_b32_e32 v207, v115
	v_pk_mul_f32 v[98:99], v[98:99], v[116:117] op_sel_hi:[1,0]
	v_pk_mul_f32 v[114:115], v[106:107], v[116:117] op_sel_hi:[1,0]
	v_pk_mul_f32 v[106:107], v[108:109], v[116:117] op_sel_hi:[1,0]
	v_pk_mul_f32 v[96:97], v[96:97], v[116:117] op_sel_hi:[1,0]
	v_pk_mul_f32 v[106:107], v[180:181], v[106:107]
	v_pk_mul_f32 v[108:109], v[182:183], v[114:115]
	s_nop 1
	v_permlane16_swap_b32_e32 v204, v106
	v_permlane16_swap_b32_e32 v205, v107
	v_permlane16_swap_b32_e32 v206, v108
	v_permlane16_swap_b32_e32 v207, v109
	v_permlane32_swap_b32_e32 v204, v106
	v_permlane32_swap_b32_e32 v205, v107
	v_permlane32_swap_b32_e32 v206, v108
	v_permlane32_swap_b32_e32 v207, v109
	v_sub_u32_e32 v203, v121, v202
	global_store_dwordx4 v203, v[204:207], s[72:73] nt
	global_store_dwordx4 v203, v[106:109], s[72:73] offset:64 nt
	s_nop 1
	v_pk_mul_f32 v[110:111], v[102:103], v[116:117] op_sel_hi:[1,0]
	v_pk_mul_f32 v[102:103], v[104:105], v[116:117] op_sel_hi:[1,0]
	v_add_u32_e32 v112, v122, v120
	v_pk_mul_f32 v[102:103], v[184:185], v[102:103]
	v_pk_mul_f32 v[104:105], v[186:187], v[110:111]
	v_mov_b32_e32 v204, v102
	v_mov_b32_e32 v205, v103
	v_mov_b32_e32 v206, v104
	v_mov_b32_e32 v207, v105
	v_pk_mul_f32 v[96:97], v[188:189], v[96:97]
	v_pk_mul_f32 v[98:99], v[190:191], v[98:99]
	s_nop 1
;   DI void operator()(g8::Acc& acc, int pm, int pn, int wr, int wc, int fr, int fq) const {
;     ...
; #pragma unroll
;     for (int ai = 0; ai < 2; ++ai)
; #pragma unroll
;       for (int m = 0; m < 4; ++m) {
;         const int row = pm * BM + ai * HALF + wr * 64 + m * 16 + fr;
;         const float rs = rsqrtf(__hip_atomic_load(ssq + row, __ATOMIC_RELAXED, __HIP_MEMORY_SCOPE_AGENT) * (1.0f / DM) + RMS_EPS);
; #pragma unroll
;         for (int bj = 0; bj < 2; ++bj) {
;           const int col8 = pn * BM + wc * 64 + bj * 32 + fq * 8; const unsigned eo = (unsigned)row * DM + (unsigned)col8;
;           gst<f32x4>(outf, eo * 4u, acc[ai][bj][m][0] * rs * gld<f32x4>(g, (unsigned)col8 * 4u));
;           gst<f32x4>(outf, eo * 4u + 16u, acc[ai][bj][m][1] * rs * gld<f32x4>(g, (unsigned)col8 * 4u + 16u));
;         }
;       }
	v_permlane16_swap_b32_e32 v204, v96
	v_permlane16_swap_b32_e32 v205, v97
	v_permlane16_swap_b32_e32 v206, v98
	v_permlane16_swap_b32_e32 v207, v99
	v_permlane32_swap_b32_e32 v204, v96
	v_permlane32_swap_b32_e32 v205, v97
	v_permlane32_swap_b32_e32 v206, v98
	v_permlane32_swap_b32_e32 v207, v99
	v_sub_u32_e32 v203, v112, v202
	global_store_dwordx4 v203, v[204:207], s[72:73] nt
	global_store_dwordx4 v203, v[96:99], s[72:73] offset:64 nt
	s_nop 1
	s_nop 0
	v_lshlrev_b32_e32 v104, 12, v100
	v_add_u32_e32 v105, v104, v141
	v_fmamk_f32 v101, v194, 0x3a800000, v163
	v_mul_f32_e32 v102, 0x4b800000, v101
	v_cmp_gt_f32_e32 vcc, s51, v101
	s_nop 1
	v_cndmask_b32_e32 v101, v101, v102, vcc
	v_rsq_f32_e32 v101, v101
	s_nop 0
	v_mul_f32_e32 v100, 0x45800000, v101
	v_cndmask_b32_e32 v100, v101, v100, vcc
	v_pk_mul_f32 v[102:103], v[146:147], v[100:101] op_sel_hi:[1,0]
	v_pk_mul_f32 v[94:95], v[94:95], v[100:101] op_sel_hi:[1,0]
	v_pk_mul_f32 v[96:97], v[176:177], v[102:103]
	v_pk_mul_f32 v[98:99], v[178:179], v[94:95]
	v_mov_b32_e32 v204, v96
	v_mov_b32_e32 v205, v97
	v_mov_b32_e32 v206, v98
	v_mov_b32_e32 v207, v99
	v_pk_mul_f32 v[82:83], v[82:83], v[100:101] op_sel_hi:[1,0]
	v_pk_mul_f32 v[98:99], v[90:91], v[100:101] op_sel_hi:[1,0]
	v_pk_mul_f32 v[90:91], v[92:93], v[100:101] op_sel_hi:[1,0]
	v_pk_mul_f32 v[80:81], v[80:81], v[100:101] op_sel_hi:[1,0]
	v_pk_mul_f32 v[90:91], v[180:181], v[90:91]
	v_pk_mul_f32 v[92:93], v[182:183], v[98:99]
	s_nop 1
	v_permlane16_swap_b32_e32 v204, v90
	v_permlane16_swap_b32_e32 v205, v91
	v_permlane16_swap_b32_e32 v206, v92
	v_permlane16_swap_b32_e32 v207, v93
	v_permlane32_swap_b32_e32 v204, v90
	v_permlane32_swap_b32_e32 v205, v91
	v_permlane32_swap_b32_e32 v206, v92
	v_permlane32_swap_b32_e32 v207, v93
	v_sub_u32_e32 v203, v105, v202
	global_store_dwordx4 v203, v[204:207], s[72:73] nt
	global_store_dwordx4 v203, v[90:93], s[72:73] offset:64 nt
	s_nop 1
	v_pk_mul_f32 v[94:95], v[86:87], v[100:101] op_sel_hi:[1,0]
	v_pk_mul_f32 v[86:87], v[88:89], v[100:101] op_sel_hi:[1,0]
	v_add_u32_e32 v96, v122, v104
	v_pk_mul_f32 v[86:87], v[184:185], v[86:87]
	v_pk_mul_f32 v[88:89], v[186:187], v[94:95]
	v_mov_b32_e32 v204, v86
	v_mov_b32_e32 v205, v87
	v_mov_b32_e32 v206, v88
	v_mov_b32_e32 v207, v89
	v_pk_mul_f32 v[80:81], v[188:189], v[80:81]
	v_pk_mul_f32 v[82:83], v[190:191], v[82:83]
	s_nop 1
	v_permlane16_swap_b32_e32 v204, v80
	v_permlane16_swap_b32_e32 v205, v81
	v_permlane16_swap_b32_e32 v206, v82
	v_permlane16_swap_b32_e32 v207, v83
	v_permlane32_swap_b32_e32 v204, v80
	v_permlane32_swap_b32_e32 v205, v81
	v_permlane32_swap_b32_e32 v206, v82
	v_permlane32_swap_b32_e32 v207, v83
	v_sub_u32_e32 v203, v96, v202
	global_store_dwordx4 v203, v[204:207], s[72:73] nt
	global_store_dwordx4 v203, v[80:83], s[72:73] offset:64 nt
	s_nop 1
	s_nop 0
	v_lshlrev_b32_e32 v88, 12, v84
	v_add_u32_e32 v89, v88, v141
	v_fmamk_f32 v85, v195, 0x3a800000, v163
	v_mul_f32_e32 v86, 0x4b800000, v85
	v_cmp_gt_f32_e32 vcc, s51, v85
	s_nop 1
	v_cndmask_b32_e32 v85, v85, v86, vcc
	v_rsq_f32_e32 v85, v85
	s_nop 0
	v_mul_f32_e32 v84, 0x45800000, v85
	v_cndmask_b32_e32 v84, v85, v84, vcc
	v_pk_mul_f32 v[86:87], v[148:149], v[84:85] op_sel_hi:[1,0]
	v_pk_mul_f32 v[78:79], v[78:79], v[84:85] op_sel_hi:[1,0]
	v_pk_mul_f32 v[80:81], v[176:177], v[86:87]
	v_pk_mul_f32 v[82:83], v[178:179], v[78:79]
	v_mov_b32_e32 v204, v80
	v_mov_b32_e32 v205, v81
	v_mov_b32_e32 v206, v82
	v_mov_b32_e32 v207, v83
	v_pk_mul_f32 v[66:67], v[66:67], v[84:85] op_sel_hi:[1,0]
	v_pk_mul_f32 v[82:83], v[74:75], v[84:85] op_sel_hi:[1,0]
	v_pk_mul_f32 v[74:75], v[76:77], v[84:85] op_sel_hi:[1,0]
	v_pk_mul_f32 v[64:65], v[64:65], v[84:85] op_sel_hi:[1,0]
	v_pk_mul_f32 v[74:75], v[180:181], v[74:75]
	v_pk_mul_f32 v[76:77], v[182:183], v[82:83]
	s_nop 1
	v_permlane16_swap_b32_e32 v204, v74
	v_permlane16_swap_b32_e32 v205, v75
	v_permlane16_swap_b32_e32 v206, v76
	v_permlane16_swap_b32_e32 v207, v77
	v_permlane32_swap_b32_e32 v204, v74
	v_permlane32_swap_b32_e32 v205, v75
	v_permlane32_swap_b32_e32 v206, v76
	v_permlane32_swap_b32_e32 v207, v77
	v_sub_u32_e32 v203, v89, v202
	global_store_dwordx4 v203, v[204:207], s[72:73] nt
	global_store_dwordx4 v203, v[74:77], s[72:73] offset:64 nt
	s_nop 1
	v_pk_mul_f32 v[78:79], v[70:71], v[84:85] op_sel_hi:[1,0]
	v_pk_mul_f32 v[70:71], v[72:73], v[84:85] op_sel_hi:[1,0]
	v_add_u32_e32 v80, v122, v88
	v_pk_mul_f32 v[70:71], v[184:185], v[70:71]
	v_pk_mul_f32 v[72:73], v[186:187], v[78:79]
	v_mov_b32_e32 v204, v70
	v_mov_b32_e32 v205, v71
	v_mov_b32_e32 v206, v72
	v_mov_b32_e32 v207, v73
	v_pk_mul_f32 v[64:65], v[188:189], v[64:65]
	v_pk_mul_f32 v[66:67], v[190:191], v[66:67]
	s_nop 1
	v_permlane16_swap_b32_e32 v204, v64
	v_permlane16_swap_b32_e32 v205, v65
	v_permlane16_swap_b32_e32 v206, v66
	v_permlane16_swap_b32_e32 v207, v67
	v_permlane32_swap_b32_e32 v204, v64
	v_permlane32_swap_b32_e32 v205, v65
	v_permlane32_swap_b32_e32 v206, v66
	v_permlane32_swap_b32_e32 v207, v67
	v_sub_u32_e32 v203, v80, v202
	global_store_dwordx4 v203, v[204:207], s[72:73] nt
	global_store_dwordx4 v203, v[64:67], s[72:73] offset:64 nt
	s_nop 1
	s_nop 0
	v_lshlrev_b32_e32 v72, 12, v68
	v_add_u32_e32 v73, v72, v141
	v_fmamk_f32 v69, v196, 0x3a800000, v163
	v_mul_f32_e32 v70, 0x4b800000, v69
	v_cmp_gt_f32_e32 vcc, s51, v69
	s_nop 1
	v_cndmask_b32_e32 v69, v69, v70, vcc
	v_rsq_f32_e32 v69, v69
	s_nop 0
	v_mul_f32_e32 v68, 0x45800000, v69
	v_cndmask_b32_e32 v68, v69, v68, vcc
	v_pk_mul_f32 v[70:71], v[150:151], v[68:69] op_sel_hi:[1,0]
	v_pk_mul_f32 v[62:63], v[62:63], v[68:69] op_sel_hi:[1,0]
	v_pk_mul_f32 v[64:65], v[176:177], v[70:71]
	v_pk_mul_f32 v[66:67], v[178:179], v[62:63]
;   DI void operator()(g8::Acc& acc, int pm, int pn, int wr, int wc, int fr, int fq) const {
;     ...
; #pragma unroll
;     for (int ai = 0; ai < 2; ++ai)
; #pragma unroll
;       for (int m = 0; m < 4; ++m) {
;         const int row = pm * BM + ai * HALF + wr * 64 + m * 16 + fr;
;         const float rs = rsqrtf(__hip_atomic_load(ssq + row, __ATOMIC_RELAXED, __HIP_MEMORY_SCOPE_AGENT) * (1.0f / DM) + RMS_EPS);
; #pragma unroll
;         for (int bj = 0; bj < 2; ++bj) {
;           const int col8 = pn * BM + wc * 64 + bj * 32 + fq * 8; const unsigned eo = (unsigned)row * DM + (unsigned)col8;
;           gst<f32x4>(outf, eo * 4u, acc[ai][bj][m][0] * rs * gld<f32x4>(g, (unsigned)col8 * 4u));
;           gst<f32x4>(outf, eo * 4u + 16u, acc[ai][bj][m][1] * rs * gld<f32x4>(g, (unsigned)col8 * 4u + 16u));
;         }
;       }
	v_mov_b32_e32 v204, v64
	v_mov_b32_e32 v205, v65
	v_mov_b32_e32 v206, v66
	v_mov_b32_e32 v207, v67
	v_pk_mul_f32 v[50:51], v[50:51], v[68:69] op_sel_hi:[1,0]
	v_pk_mul_f32 v[66:67], v[58:59], v[68:69] op_sel_hi:[1,0]
	v_pk_mul_f32 v[58:59], v[60:61], v[68:69] op_sel_hi:[1,0]
	v_pk_mul_f32 v[48:49], v[48:49], v[68:69] op_sel_hi:[1,0]
	v_pk_mul_f32 v[58:59], v[180:181], v[58:59]
	v_pk_mul_f32 v[60:61], v[182:183], v[66:67]
	s_nop 1
	v_permlane16_swap_b32_e32 v204, v58
	v_permlane16_swap_b32_e32 v205, v59
	v_permlane16_swap_b32_e32 v206, v60
	v_permlane16_swap_b32_e32 v207, v61
	v_permlane32_swap_b32_e32 v204, v58
	v_permlane32_swap_b32_e32 v205, v59
	v_permlane32_swap_b32_e32 v206, v60
	v_permlane32_swap_b32_e32 v207, v61
	v_sub_u32_e32 v203, v73, v202
	global_store_dwordx4 v203, v[204:207], s[72:73] nt
	global_store_dwordx4 v203, v[58:61], s[72:73] offset:64 nt
	s_nop 1
	v_pk_mul_f32 v[62:63], v[54:55], v[68:69] op_sel_hi:[1,0]
	v_pk_mul_f32 v[54:55], v[56:57], v[68:69] op_sel_hi:[1,0]
	v_add_u32_e32 v64, v122, v72
	v_pk_mul_f32 v[54:55], v[184:185], v[54:55]
	v_pk_mul_f32 v[56:57], v[186:187], v[62:63]
	v_mov_b32_e32 v204, v54
	v_mov_b32_e32 v205, v55
	v_mov_b32_e32 v206, v56
	v_mov_b32_e32 v207, v57
	v_pk_mul_f32 v[48:49], v[188:189], v[48:49]
	v_pk_mul_f32 v[50:51], v[190:191], v[50:51]
	s_nop 1
	v_permlane16_swap_b32_e32 v204, v48
	v_permlane16_swap_b32_e32 v205, v49
	v_permlane16_swap_b32_e32 v206, v50
	v_permlane16_swap_b32_e32 v207, v51
	v_permlane32_swap_b32_e32 v204, v48
	v_permlane32_swap_b32_e32 v205, v49
	v_permlane32_swap_b32_e32 v206, v50
	v_permlane32_swap_b32_e32 v207, v51
	v_sub_u32_e32 v203, v64, v202
	global_store_dwordx4 v203, v[204:207], s[72:73] nt
	global_store_dwordx4 v203, v[48:51], s[72:73] offset:64 nt
	s_nop 1
	s_nop 0
	v_lshlrev_b32_e32 v56, 12, v52
	v_add_u32_e32 v57, v56, v141
	v_fmamk_f32 v53, v197, 0x3a800000, v163
	v_mul_f32_e32 v54, 0x4b800000, v53
	v_cmp_gt_f32_e32 vcc, s51, v53
	s_nop 1
	v_cndmask_b32_e32 v53, v53, v54, vcc
	v_rsq_f32_e32 v53, v53
	s_nop 0
	v_mul_f32_e32 v52, 0x45800000, v53
	v_cndmask_b32_e32 v52, v53, v52, vcc
	v_pk_mul_f32 v[54:55], v[152:153], v[52:53] op_sel_hi:[1,0]
	v_pk_mul_f32 v[46:47], v[46:47], v[52:53] op_sel_hi:[1,0]
	v_pk_mul_f32 v[48:49], v[176:177], v[54:55]
	v_pk_mul_f32 v[50:51], v[178:179], v[46:47]
	v_mov_b32_e32 v204, v48
	v_mov_b32_e32 v205, v49
	v_mov_b32_e32 v206, v50
	v_mov_b32_e32 v207, v51
	v_pk_mul_f32 v[34:35], v[34:35], v[52:53] op_sel_hi:[1,0]
	v_pk_mul_f32 v[50:51], v[42:43], v[52:53] op_sel_hi:[1,0]
	v_pk_mul_f32 v[42:43], v[44:45], v[52:53] op_sel_hi:[1,0]
	v_pk_mul_f32 v[32:33], v[32:33], v[52:53] op_sel_hi:[1,0]
	v_pk_mul_f32 v[42:43], v[180:181], v[42:43]
	v_pk_mul_f32 v[44:45], v[182:183], v[50:51]
	s_nop 1
	v_permlane16_swap_b32_e32 v204, v42
	v_permlane16_swap_b32_e32 v205, v43
	v_permlane16_swap_b32_e32 v206, v44
	v_permlane16_swap_b32_e32 v207, v45
	v_permlane32_swap_b32_e32 v204, v42
	v_permlane32_swap_b32_e32 v205, v43
	v_permlane32_swap_b32_e32 v206, v44
	v_permlane32_swap_b32_e32 v207, v45
	v_sub_u32_e32 v203, v57, v202
	global_store_dwordx4 v203, v[204:207], s[72:73] nt
	global_store_dwordx4 v203, v[42:45], s[72:73] offset:64 nt
	s_nop 1
	v_pk_mul_f32 v[46:47], v[38:39], v[52:53] op_sel_hi:[1,0]
	v_pk_mul_f32 v[38:39], v[40:41], v[52:53] op_sel_hi:[1,0]
	v_add_u32_e32 v48, v122, v56
	v_pk_mul_f32 v[38:39], v[184:185], v[38:39]
	v_pk_mul_f32 v[40:41], v[186:187], v[46:47]
	v_mov_b32_e32 v204, v38
	v_mov_b32_e32 v205, v39
	v_mov_b32_e32 v206, v40
	v_mov_b32_e32 v207, v41
	v_pk_mul_f32 v[32:33], v[188:189], v[32:33]
	v_pk_mul_f32 v[34:35], v[190:191], v[34:35]
	s_nop 1
	v_permlane16_swap_b32_e32 v204, v32
	v_permlane16_swap_b32_e32 v205, v33
	v_permlane16_swap_b32_e32 v206, v34
	v_permlane16_swap_b32_e32 v207, v35
	v_permlane32_swap_b32_e32 v204, v32
	v_permlane32_swap_b32_e32 v205, v33
	v_permlane32_swap_b32_e32 v206, v34
	v_permlane32_swap_b32_e32 v207, v35
	v_sub_u32_e32 v203, v48, v202
	global_store_dwordx4 v203, v[204:207], s[72:73] nt
	global_store_dwordx4 v203, v[32:35], s[72:73] offset:64 nt
	s_nop 1
	s_nop 0
	v_lshlrev_b32_e32 v40, 12, v36
	v_add_u32_e32 v41, v40, v141
	v_fmamk_f32 v37, v198, 0x3a800000, v163
	v_mul_f32_e32 v38, 0x4b800000, v37
	v_cmp_gt_f32_e32 vcc, s51, v37
	s_nop 1
	v_cndmask_b32_e32 v37, v37, v38, vcc
	v_rsq_f32_e32 v37, v37
	s_nop 0
	v_mul_f32_e32 v36, 0x45800000, v37
;   DI void operator()(g8::Acc& acc, int pm, int pn, int wr, int wc, int fr, int fq) const {
;     ...
; #pragma unroll
;     for (int ai = 0; ai < 2; ++ai)
; #pragma unroll
;       for (int m = 0; m < 4; ++m) {
;         const int row = pm * BM + ai * HALF + wr * 64 + m * 16 + fr;
;         const float rs = rsqrtf(__hip_atomic_load(ssq + row, __ATOMIC_RELAXED, __HIP_MEMORY_SCOPE_AGENT) * (1.0f / DM) + RMS_EPS);
; #pragma unroll
;         for (int bj = 0; bj < 2; ++bj) {
;           const int col8 = pn * BM + wc * 64 + bj * 32 + fq * 8; const unsigned eo = (unsigned)row * DM + (unsigned)col8;
;           gst<f32x4>(outf, eo * 4u, acc[ai][bj][m][0] * rs * gld<f32x4>(g, (unsigned)col8 * 4u));
;           gst<f32x4>(outf, eo * 4u + 16u, acc[ai][bj][m][1] * rs * gld<f32x4>(g, (unsigned)col8 * 4u + 16u));
;         }
;       }
	v_cndmask_b32_e32 v36, v37, v36, vcc
	v_pk_mul_f32 v[38:39], v[154:155], v[36:37] op_sel_hi:[1,0]
	v_pk_mul_f32 v[30:31], v[30:31], v[36:37] op_sel_hi:[1,0]
	v_pk_mul_f32 v[32:33], v[176:177], v[38:39]
	v_pk_mul_f32 v[34:35], v[178:179], v[30:31]
	v_mov_b32_e32 v204, v32
	v_mov_b32_e32 v205, v33
	v_mov_b32_e32 v206, v34
	v_mov_b32_e32 v207, v35
	v_pk_mul_f32 v[18:19], v[18:19], v[36:37] op_sel_hi:[1,0]
	v_pk_mul_f32 v[34:35], v[26:27], v[36:37] op_sel_hi:[1,0]
	v_pk_mul_f32 v[26:27], v[28:29], v[36:37] op_sel_hi:[1,0]
	v_pk_mul_f32 v[16:17], v[16:17], v[36:37] op_sel_hi:[1,0]
	v_pk_mul_f32 v[26:27], v[180:181], v[26:27]
	v_pk_mul_f32 v[28:29], v[182:183], v[34:35]
	s_nop 1
	v_permlane16_swap_b32_e32 v204, v26
	v_permlane16_swap_b32_e32 v205, v27
	v_permlane16_swap_b32_e32 v206, v28
	v_permlane16_swap_b32_e32 v207, v29
	v_permlane32_swap_b32_e32 v204, v26
	v_permlane32_swap_b32_e32 v205, v27
	v_permlane32_swap_b32_e32 v206, v28
	v_permlane32_swap_b32_e32 v207, v29
	v_sub_u32_e32 v203, v41, v202
	global_store_dwordx4 v203, v[204:207], s[72:73] nt
	global_store_dwordx4 v203, v[26:29], s[72:73] offset:64 nt
	s_nop 1
	v_pk_mul_f32 v[30:31], v[22:23], v[36:37] op_sel_hi:[1,0]
	v_pk_mul_f32 v[22:23], v[24:25], v[36:37] op_sel_hi:[1,0]
	v_add_u32_e32 v32, v122, v40
	v_pk_mul_f32 v[22:23], v[184:185], v[22:23]
	v_pk_mul_f32 v[24:25], v[186:187], v[30:31]
	v_mov_b32_e32 v204, v22
	v_mov_b32_e32 v205, v23
	v_mov_b32_e32 v206, v24
	v_mov_b32_e32 v207, v25
	v_pk_mul_f32 v[16:17], v[188:189], v[16:17]
	v_pk_mul_f32 v[18:19], v[190:191], v[18:19]
	s_nop 1
	v_permlane16_swap_b32_e32 v204, v16
	v_permlane16_swap_b32_e32 v205, v17
	v_permlane16_swap_b32_e32 v206, v18
	v_permlane16_swap_b32_e32 v207, v19
	v_permlane32_swap_b32_e32 v204, v16
	v_permlane32_swap_b32_e32 v205, v17
	v_permlane32_swap_b32_e32 v206, v18
	v_permlane32_swap_b32_e32 v207, v19
	v_sub_u32_e32 v203, v32, v202
	global_store_dwordx4 v203, v[204:207], s[72:73] nt
	global_store_dwordx4 v203, v[16:19], s[72:73] offset:64 nt
	s_nop 1
	s_nop 0
	v_fmamk_f32 v21, v199, 0x3a800000, v163
	v_mul_f32_e32 v22, 0x4b800000, v21
	v_cmp_gt_f32_e32 vcc, s51, v21
	s_nop 1
	v_cndmask_b32_e32 v21, v21, v22, vcc
	v_rsq_f32_e32 v21, v21
	v_lshlrev_b32_e32 v22, 12, v20
	v_add_u32_e32 v23, v22, v141
	v_mul_f32_e32 v20, 0x45800000, v21
	v_cndmask_b32_e32 v20, v21, v20, vcc
	v_pk_mul_f32 v[12:13], v[12:13], v[20:21] op_sel_hi:[1,0]
	v_pk_mul_f32 v[14:15], v[14:15], v[20:21] op_sel_hi:[1,0]
	v_pk_mul_f32 v[12:13], v[176:177], v[12:13]
	v_pk_mul_f32 v[14:15], v[178:179], v[14:15]
	v_mov_b32_e32 v204, v12
	v_mov_b32_e32 v205, v13
	v_mov_b32_e32 v206, v14
	v_mov_b32_e32 v207, v15
	v_pk_mul_f32 v[10:11], v[10:11], v[20:21] op_sel_hi:[1,0]
	v_pk_mul_f32 v[8:9], v[8:9], v[20:21] op_sel_hi:[1,0]
	v_pk_mul_f32 v[6:7], v[6:7], v[20:21] op_sel_hi:[1,0]
	v_pk_mul_f32 v[4:5], v[4:5], v[20:21] op_sel_hi:[1,0]
	v_pk_mul_f32 v[2:3], v[2:3], v[20:21] op_sel_hi:[1,0]
	v_pk_mul_f32 v[0:1], v[0:1], v[20:21] op_sel_hi:[1,0]
	s_andn2_b64 vcc, exec, s[28:29]
	v_pk_mul_f32 v[8:9], v[180:181], v[8:9]
	v_pk_mul_f32 v[10:11], v[182:183], v[10:11]
	s_nop 1
	v_permlane16_swap_b32_e32 v204, v8
	v_permlane16_swap_b32_e32 v205, v9
	v_permlane16_swap_b32_e32 v206, v10
	v_permlane16_swap_b32_e32 v207, v11
	v_permlane32_swap_b32_e32 v204, v8
	v_permlane32_swap_b32_e32 v205, v9
	v_permlane32_swap_b32_e32 v206, v10
	v_permlane32_swap_b32_e32 v207, v11
	v_sub_u32_e32 v203, v23, v202
	global_store_dwordx4 v203, v[204:207], s[72:73] nt
	global_store_dwordx4 v203, v[8:11], s[72:73] offset:64 nt
	s_nop 1
	v_add_u32_e32 v12, v122, v22
	v_pk_mul_f32 v[4:5], v[184:185], v[4:5]
	v_pk_mul_f32 v[6:7], v[186:187], v[6:7]
	v_mov_b32_e32 v204, v4
	v_mov_b32_e32 v205, v5
	v_mov_b32_e32 v206, v6
	v_mov_b32_e32 v207, v7
	v_pk_mul_f32 v[0:1], v[188:189], v[0:1]
	v_pk_mul_f32 v[2:3], v[190:191], v[2:3]
	s_nop 1
	v_permlane16_swap_b32_e32 v204, v0
	v_permlane16_swap_b32_e32 v205, v1
	v_permlane16_swap_b32_e32 v206, v2
	v_permlane16_swap_b32_e32 v207, v3
	v_permlane32_swap_b32_e32 v204, v0
	v_permlane32_swap_b32_e32 v205, v1
	v_permlane32_swap_b32_e32 v206, v2
	v_permlane32_swap_b32_e32 v207, v3
	v_sub_u32_e32 v203, v12, v202
	global_store_dwordx4 v203, v[204:207], s[72:73] nt
	global_store_dwordx4 v203, v[0:3], s[72:73] offset:64 nt
	s_nop 1
	s_cbranch_vccnz .LBB0_892
	s_andn2_b64 vcc, exec, s[6:7]
	s_cbranch_vccnz .LBB0_891
	s_barrier
	s_branch .LBB0_891
